# strategy 4 on phase 2: static s_setprio 1 for waves 4-7 during the z post-processing row loop
# speedup vs baseline: 1.0034x; 1.0034x over previous
.LBB0_183:
	s_cmp_lt_i32 s34, 3
	s_cselect_b64 s[14:15], -1, 0
	s_and_b64 s[6:7], s[14:15], s[6:7]
	s_andn2_b64 vcc, exec, s[6:7]
	v_lshrrev_b32_e32 v130, 6, v0
	s_cbranch_vccnz .LBB0_206
	s_waitcnt lgkmcnt(0)
	s_load_dword s3, s[0:1], 0xd8
	s_lshl_b32 s12, s2, 3
	v_or_b32_e32 v1, s12, v130
	s_movk_i32 s6, 0x2000
	v_cmp_gt_i32_e32 vcc, s6, v1
	s_and_saveexec_b64 s[16:17], vcc
	s_cbranch_execz .LBB0_203
	v_readfirstlane_b32 s85, v130
	s_nop 1
	s_cmp_lt_u32 s85, 4
	s_cbranch_scc1 .Lp2_noprio
	s_setprio 1
.Lp2_noprio:
	v_readfirstlane_b32 s85, v130
	s_lshl_b32 s84, s2, 3
	s_nop 0
	s_add_u32 s84, s84, s85
	s_cmp_lt_u32 s84, 0x400
	s_cbranch_scc0 .Lvbp_skip
	v_and_b32_e32 v210, 63, v0
	v_lshlrev_b32_e32 v210, 1, v210
	s_lshr_b32 s86, s84, 9
	s_bfe_u32 s87, s84, 0x70002
	s_and_b32 s90, s84, 3
	s_lshl_b32 s91, s86, 7
	s_add_u32 s91, s91, s87
	s_mul_i32 s91, s91, 0x50000
	s_lshl_b32 s92, s90, 7
	s_add_u32 s91, s91, s92
	s_add_u32 s91, s91, 0x2600
	s_add_u32 s88, s70, s91
	s_addc_u32 s89, s71, 0
	s_add_u32 s88, s88, 0x7900000
	s_addc_u32 s89, s89, 0
	global_load_ushort v211, v210, s[88:89]
	s_add_u32 s88, s88, 0x2800
	s_addc_u32 s89, s89, 0
	global_load_ushort v212, v210, s[88:89]
	s_add_u32 s88, s88, 0x2800
	s_addc_u32 s89, s89, 0
	global_load_ushort v213, v210, s[88:89]
	s_add_u32 s88, s88, 0x2800
	s_addc_u32 s89, s89, 0
	global_load_ushort v214, v210, s[88:89]
	s_add_u32 s88, s88, 0x2800
	s_addc_u32 s89, s89, 0
	global_load_ushort v215, v210, s[88:89]
	s_add_u32 s88, s88, 0x2800
	s_addc_u32 s89, s89, 0
	global_load_ushort v216, v210, s[88:89]
	s_add_u32 s88, s88, 0x2800
	s_addc_u32 s89, s89, 0
	global_load_ushort v217, v210, s[88:89]
	s_add_u32 s88, s88, 0x2800
	s_addc_u32 s89, s89, 0
	global_load_ushort v218, v210, s[88:89]
	s_add_u32 s88, s88, 0x2800
	s_addc_u32 s89, s89, 0
	global_load_ushort v219, v210, s[88:89]
	s_add_u32 s88, s88, 0x2800
	s_addc_u32 s89, s89, 0
	global_load_ushort v220, v210, s[88:89]
	s_add_u32 s88, s88, 0x2800
	s_addc_u32 s89, s89, 0
	global_load_ushort v221, v210, s[88:89]
	s_add_u32 s88, s88, 0x2800
	s_addc_u32 s89, s89, 0
	global_load_ushort v222, v210, s[88:89]
	s_add_u32 s88, s88, 0x2800
	s_addc_u32 s89, s89, 0
	global_load_ushort v223, v210, s[88:89]
	s_add_u32 s88, s88, 0x2800
	s_addc_u32 s89, s89, 0
	global_load_ushort v224, v210, s[88:89]
	s_add_u32 s88, s88, 0x2800
	s_addc_u32 s89, s89, 0
	global_load_ushort v225, v210, s[88:89]
	s_add_u32 s88, s88, 0x2800
	s_addc_u32 s89, s89, 0
	global_load_ushort v226, v210, s[88:89]
	s_add_u32 s88, s88, 0x2800
	s_addc_u32 s89, s89, 0
	global_load_ushort v227, v210, s[88:89]
	s_add_u32 s88, s88, 0x2800
	s_addc_u32 s89, s89, 0
	global_load_ushort v228, v210, s[88:89]
	s_add_u32 s88, s88, 0x2800
	s_addc_u32 s89, s89, 0
	global_load_ushort v229, v210, s[88:89]
	s_add_u32 s88, s88, 0x2800
	s_addc_u32 s89, s89, 0
	global_load_ushort v230, v210, s[88:89]
	s_add_u32 s88, s88, 0x2800
	s_addc_u32 s89, s89, 0
	global_load_ushort v231, v210, s[88:89]
	s_add_u32 s88, s88, 0x2800
	s_addc_u32 s89, s89, 0
	global_load_ushort v232, v210, s[88:89]
	s_add_u32 s88, s88, 0x2800
	s_addc_u32 s89, s89, 0
	global_load_ushort v233, v210, s[88:89]
	s_add_u32 s88, s88, 0x2800
	s_addc_u32 s89, s89, 0
	global_load_ushort v234, v210, s[88:89]
	s_add_u32 s88, s88, 0x2800
	s_addc_u32 s89, s89, 0
	global_load_ushort v235, v210, s[88:89]
	s_add_u32 s88, s88, 0x2800
	s_addc_u32 s89, s89, 0
	global_load_ushort v236, v210, s[88:89]
	s_add_u32 s88, s88, 0x2800
	s_addc_u32 s89, s89, 0
	global_load_ushort v237, v210, s[88:89]
	s_add_u32 s88, s88, 0x2800
	s_addc_u32 s89, s89, 0
	global_load_ushort v238, v210, s[88:89]
	s_add_u32 s88, s88, 0x2800
	s_addc_u32 s89, s89, 0
	global_load_ushort v239, v210, s[88:89]
	s_add_u32 s88, s88, 0x2800
	s_addc_u32 s89, s89, 0
	global_load_ushort v240, v210, s[88:89]
	s_add_u32 s88, s88, 0x2800
	s_addc_u32 s89, s89, 0
	global_load_ushort v241, v210, s[88:89]
	s_add_u32 s88, s88, 0x2800
	s_addc_u32 s89, s89, 0
	global_load_ushort v242, v210, s[88:89]

.LBB0_203:
	s_or_b64 exec, exec, s[16:17]
	s_setprio 0
	s_load_dword s6, s[0:1], 0xd8
	v_and_b32_e32 v1, 63, v0
	v_lshlrev_b32_e32 v2, 1, v1
	v_lshlrev_b32_e32 v3, 6, v1
	v_readfirstlane_b32 s7, v130
	s_lshl_b32 s8, s2, 3
	s_nop 0
	s_add_u32 s8, s8, s7
	s_waitcnt lgkmcnt(0)
	s_lshl_b32 s6, s6, 3
	s_cmp_lt_u32 s8, 0x400
	s_cbranch_scc0 .Lvb_done

.Lat_pv_done:
	s_nop 7
	v_cvt_pk_bf16_f32 v22, v240, v240
	v_cvt_pk_bf16_f32 v23, v241, v241
	v_cvt_pk_bf16_f32 v24, v242, v242
	v_cvt_pk_bf16_f32 v25, v243, v243
	v_cvt_pk_bf16_f32 v26, v244, v244
	v_cvt_pk_bf16_f32 v27, v245, v245
	v_cvt_pk_bf16_f32 v28, v246, v246
	v_cvt_pk_bf16_f32 v29, v247, v247
	v_cvt_pk_bf16_f32 v134, v248, v248
	v_cvt_pk_bf16_f32 v135, v249, v249
	v_cvt_pk_bf16_f32 v136, v250, v250
	v_cvt_pk_bf16_f32 v137, v251, v251
	v_cvt_pk_bf16_f32 v138, v120, v120
	v_cvt_pk_bf16_f32 v139, v121, v121
	v_cvt_pk_bf16_f32 v150, v122, v122
	v_cvt_pk_bf16_f32 v151, v123, v123
	global_store_short v17, v22, s[20:21]
	global_store_short v17, v23, s[20:21] offset:2048
	global_store_short v18, v24, s[20:21]
	global_store_short v18, v25, s[20:21] offset:2048
	global_store_short v17, v26, s[20:21] offset:32
	global_store_short v17, v27, s[20:21] offset:2080
	global_store_short v18, v28, s[20:21] offset:32
	global_store_short v18, v29, s[20:21] offset:2080
	global_store_short v17, v134, s[20:21] offset:64
	global_store_short v17, v135, s[20:21] offset:2112
	global_store_short v18, v136, s[20:21] offset:64
	global_store_short v18, v137, s[20:21] offset:2112
	global_store_short v17, v138, s[20:21] offset:96
	global_store_short v17, v139, s[20:21] offset:2144
	global_store_short v18, v150, s[20:21] offset:96
	global_store_short v18, v151, s[20:21] offset:2144
	s_add_u32 s3, s3, s6
	s_cmp_lt_u32 s3, 0x2000
	s_cbranch_scc1 .Lat_loop
	v_and_b32_e32 v10, 15, v0
	s_add_u32 s74, s0, 0xd8
	s_addc_u32 s75, s1, 0
	v_mov_b64_e32 v[2:3], s[74:75]
	s_mov_b64 s[64:65], exec
	s_nop 0
	s_nop 0
	s_nop 0
	s_nop 0
	s_nop 0
	s_nop 0
	s_nop 0
	s_nop 0
	s_nop 0
	s_nop 0
	s_nop 0
	s_nop 0
	s_nop 0
	s_nop 0
	s_nop 0
	s_nop 0
	s_nop 0
	s_nop 0
	s_nop 0
	s_nop 0
	s_nop 0
	s_nop 0
	s_nop 0
	s_nop 0
	s_nop 0
	s_nop 0
	s_nop 0
	s_nop 0
	s_nop 0
	s_nop 0
	s_nop 0
	s_nop 0
	s_nop 0
	s_nop 0
	s_nop 0
	s_nop 0
	s_nop 0
	s_nop 0
	s_nop 0
	s_nop 0
	s_nop 0
	s_nop 0
	s_nop 0
	s_nop 0
	s_nop 0
	s_nop 0
